# v101 + P7 (Hyena) phase code moved by 32 bytes (224-byte compensation at the next phase entry); repeat-amplified scan showed P7 about 4 percent faster at this placement
# baseline (speedup 1.0000x reference)
.LBB0_2194:
	s_nop 0
	s_nop 0
	s_nop 0
	s_nop 0
	s_nop 0
	s_nop 0
	s_nop 0
	s_nop 0
	s_cmp_lt_i32 s84, 8
	s_cselect_b64 s[0:1], -1, 0
	s_cmp_gt_i32 s85, 7
	s_cselect_b64 s[2:3], -1, 0
	s_and_b64 s[0:1], s[0:1], s[2:3]
	s_andn2_b64 vcc, exec, s[0:1]
	s_cbranch_vccnz .LBB0_2406
	s_add_u32 s6, s30, 0x14700000
	s_addc_u32 s7, s31, 0
	s_add_u32 s33, s30, 0x21d800
	s_addc_u32 s44, s31, 0
	s_cmpk_lt_i32 s96, 0x200
	s_cselect_b64 s[18:19], -1, 0
	s_lshl_b32 s4, s88, 9
	s_ashr_i32 s5, s4, 31
	v_readlane_b32 s3, v254, 1
	s_cmp_lt_u32 s3, 64
	s_cselect_b64 s[0:1], -1, 0
	s_lshr_b32 s38, s3, 8
	s_add_i32 s3, s88, 8
	s_lshr_b32 s20, s3, 2
	s_add_i32 s3, s88, 16
	s_lshr_b32 s40, s3, 2
	s_add_i32 s3, s88, 24
	s_lshr_b32 s50, s3, 2
	s_add_i32 s3, s88, 32
	s_lshr_b32 s52, s3, 2
	s_add_i32 s3, s88, 40
	s_lshr_b32 s54, s3, 2
	s_add_i32 s3, s88, 48
	s_lshr_b32 s56, s3, 2
	s_add_i32 s3, s88, 56
	s_mov_b32 s39, 0
	s_and_b32 s2, s4, 0x600
	s_lshr_b32 s60, s3, 2
	s_lshl_b32 s3, s88, 10
	v_cmp_gt_u32_e32 vcc, 4, v230
	s_lshl_b32 s2, s2, 1
	s_mov_b32 s21, s39
	s_mov_b32 s41, s39
	s_mov_b32 s51, s39
	s_mov_b32 s53, s39
	s_mov_b32 s55, s39
	s_mov_b32 s57, s39
	s_mov_b32 s61, s39
	s_add_i32 s46, s3, 0
	s_and_b64 s[0:1], vcc, s[0:1]
	s_add_i32 s45, s2, 0
	s_lshl_b64 s[8:9], s[38:39], 15
	s_lshl_b64 s[10:11], s[20:21], 15
	s_lshl_b64 s[12:13], s[40:41], 15
	s_lshl_b64 s[14:15], s[50:51], 15
	s_lshl_b64 s[16:17], s[52:53], 15
	s_lshl_b64 s[24:25], s[54:55], 15
	s_lshl_b64 s[34:35], s[56:57], 15
	s_lshl_b64 s[36:37], s[60:61], 15
	s_add_i32 s46, s46, 0x20200
	v_lshlrev_b32_e32 v1, 3, v230
	s_cmpk_gt_i32 s96, 0x1ff
	v_mov_b32_e32 v139, 0
	s_mul_i32 s47, s38, 0x1010
	s_mul_i32 s48, s20, 0x1010
	s_mul_i32 s49, s40, 0x1010
	s_mulk_i32 s50, 0x1010
	s_mul_i32 s51, s52, 0x1010
	s_mul_i32 s52, s54, 0x1010
	s_mul_i32 s53, s56, 0x1010
	s_mul_i32 s54, s60, 0x1010
	v_lshlrev_b32_e32 v138, 1, v1
	s_waitcnt lgkmcnt(0)
	s_barrier
	s_cbranch_scc1 .LBB0_2199
	s_mul_i32 s20, s96, 0x2040
	s_mul_hi_u32 s3, s96, 0x2040
	s_add_u32 s40, s33, s20
	s_addc_u32 s41, s44, s3
	s_lshl_b64 s[20:21], s[4:5], 1
	s_add_u32 s20, s40, s20
	s_addc_u32 s21, s41, s21
	s_add_u32 s56, s6, s2
	s_addc_u32 s57, s7, 0
	s_waitcnt vmcnt(15)
	v_lshl_add_u64 v[2:3], s[56:57], 0, v[138:139]
	s_ashr_i32 s56, s96, 3
	s_ashr_i32 s57, s56, 31
	v_lshl_add_u64 v[4:5], v[2:3], 0, s[36:37]
	s_lshl_b64 s[56:57], s[56:57], 19
	s_lshl_b32 s3, s96, 12
	s_waitcnt vmcnt(14)
	v_lshl_add_u64 v[6:7], v[2:3], 0, s[34:35]
	v_lshl_add_u64 v[8:9], v[2:3], 0, s[24:25]
	s_waitcnt vmcnt(13)
	v_lshl_add_u64 v[10:11], v[2:3], 0, s[16:17]
	v_lshl_add_u64 v[12:13], v[2:3], 0, s[14:15]
	s_waitcnt vmcnt(12)
	v_lshl_add_u64 v[14:15], v[2:3], 0, s[12:13]
	v_lshl_add_u64 v[16:17], v[2:3], 0, s[10:11]
	v_lshl_add_u64 v[2:3], v[2:3], 0, s[8:9]
	s_and_b32 s38, s3, 0x7000
	v_lshl_add_u64 v[2:3], v[2:3], 0, s[56:57]
	v_lshl_add_u64 v[16:17], v[16:17], 0, s[56:57]
	v_lshl_add_u64 v[2:3], v[2:3], 0, s[38:39]
	s_add_i32 m0, s45, s47
	v_lshl_add_u64 v[14:15], v[14:15], 0, s[56:57]
	v_lshl_add_u64 v[16:17], v[16:17], 0, s[38:39]
	global_load_lds_dwordx4 v[2:3], off
	s_add_i32 m0, s45, s48
	v_lshl_add_u64 v[12:13], v[12:13], 0, s[56:57]
	v_lshl_add_u64 v[14:15], v[14:15], 0, s[38:39]
	global_load_lds_dwordx4 v[16:17], off
	s_add_i32 m0, s45, s49
	v_lshl_add_u64 v[10:11], v[10:11], 0, s[56:57]
	v_lshl_add_u64 v[12:13], v[12:13], 0, s[38:39]
	global_load_lds_dwordx4 v[14:15], off
	s_add_i32 m0, s45, s50
	v_lshl_add_u64 v[8:9], v[8:9], 0, s[56:57]
	v_lshl_add_u64 v[10:11], v[10:11], 0, s[38:39]
	global_load_lds_dwordx4 v[12:13], off
	s_add_i32 m0, s45, s51
	v_lshl_add_u64 v[6:7], v[6:7], 0, s[56:57]
	v_lshl_add_u64 v[8:9], v[8:9], 0, s[38:39]
	global_load_lds_dwordx4 v[10:11], off
	s_add_i32 m0, s45, s52
	v_lshl_add_u64 v[4:5], v[4:5], 0, s[56:57]
	v_lshl_add_u64 v[6:7], v[6:7], 0, s[38:39]
	global_load_lds_dwordx4 v[8:9], off
	s_add_i32 m0, s45, s53
	v_lshl_add_u64 v[4:5], v[4:5], 0, s[38:39]
	global_load_lds_dwordx4 v[6:7], off
	s_add_i32 m0, s45, s54
	s_nop 0
	global_load_lds_dwordx4 v[4:5], off
	s_mov_b32 m0, s46
	s_nop 0
	global_load_lds_dwordx4 v138, s[20:21]
	s_and_saveexec_b64 s[38:39], s[0:1]
	s_cbranch_execz .LBB0_2198
	v_mov_b32_e32 v139, 0
	v_lshl_add_u64 v[2:3], s[40:41], 0, v[138:139]
	s_mov_b64 s[20:21], 0x2000
	v_lshl_add_u64 v[2:3], v[2:3], 0, s[20:21]
	s_add_i32 m0, 0, 0x22200
	s_nop 0
	global_load_lds_dwordx4 v[2:3], off

.LBB0_2406:
	s_nop 0
	s_nop 0
	s_nop 0
	s_nop 0
	s_nop 0
	s_nop 0
	s_nop 0
	s_nop 0
	s_nop 0
	s_nop 0
	s_nop 0
	s_nop 0
	s_nop 0
	s_nop 0
	s_nop 0
	s_nop 0
	s_nop 0
	s_nop 0
	s_nop 0
	s_nop 0
	s_nop 0
	s_nop 0
	s_nop 0
	s_nop 0
	s_nop 0
	s_nop 0
	s_nop 0
	s_nop 0
	s_nop 0
	s_nop 0
	s_nop 0
	s_nop 0
	s_nop 0
	s_nop 0
	s_nop 0
	s_nop 0
	s_nop 0
	s_nop 0
	s_nop 0
	s_nop 0
	s_nop 0
	s_nop 0
	s_nop 0
	s_nop 0
	s_nop 0
	s_nop 0
	s_nop 0
	s_nop 0
	s_nop 0
	s_nop 0
	s_nop 0
	s_nop 0
	s_nop 0
	s_nop 0
	s_nop 0
	s_nop 0
	s_cmp_lt_i32 s84, 9
	s_cselect_b64 s[0:1], -1, 0
	s_cmp_gt_i32 s85, 8
	s_cselect_b64 s[2:3], -1, 0
	s_and_b64 s[0:1], s[0:1], s[2:3]
	s_andn2_b64 vcc, exec, s[0:1]
	s_cbranch_vccnz .LBB0_2611
	s_lshl_b32 s2, s22, 5
	s_cmpk_gt_i32 s78, 0x1fff
	s_cbranch_scc1 .LBB0_2410
	v_lshlrev_b32_e32 v1, 5, v230
	v_and_b32_e32 v1, 0x1e0, v1
	global_load_dwordx4 v[2:5], v1, s[42:43]
	global_load_dwordx4 v[6:9], v1, s[42:43] offset:16
	v_mbcnt_lo_u32_b32 v1, -1, 0
	s_waitcnt vmcnt(15)
	v_mbcnt_hi_u32_b32 v10, -1, v1
	v_and_b32_e32 v11, 64, v10
	v_xor_b32_e32 v1, 1, v10
	v_add_u32_e32 v11, 64, v11
	s_lshl_b32 s4, s78, 2
	v_cmp_lt_i32_e32 vcc, v1, v11
	v_xor_b32_e32 v12, 2, v10
	s_ashr_i32 s5, s4, 31
	v_cndmask_b32_e32 v1, v10, v1, vcc
	v_cmp_lt_i32_e32 vcc, v12, v11
	s_lshl_b64 s[0:1], s[4:5], 11
	s_add_u32 s6, s30, s0
	v_cndmask_b32_e32 v12, v10, v12, vcc
	s_waitcnt vmcnt(13)
	v_lshlrev_b32_e32 v20, 2, v12
	v_xor_b32_e32 v12, 4, v10
	v_cmp_lt_i32_e32 vcc, v12, v11
	s_addc_u32 s7, s31, s1
	s_ashr_i32 s3, s2, 31
	v_cndmask_b32_e32 v12, v10, v12, vcc
	s_lshl_b64 s[8:9], s[2:3], 11
	s_lshl_b64 s[0:1], s[4:5], 10
	v_lshlrev_b32_e32 v21, 2, v12
	v_xor_b32_e32 v12, 8, v10
	s_add_u32 s10, s28, s0
	v_cmp_lt_i32_e32 vcc, v12, v11
	s_addc_u32 s11, s29, s1
	s_lshl_b64 s[12:13], s[2:3], 10
	v_cndmask_b32_e32 v10, v10, v12, vcc
	s_add_u32 s14, s30, s0
	v_lshlrev_b32_e32 v1, 2, v1
	s_waitcnt vmcnt(12)
	v_lshlrev_b32_e32 v22, 2, v10
	v_lshlrev_b32_e32 v10, 4, v230
	v_mov_b32_e32 v11, 0
	s_addc_u32 s15, s31, s1
	v_mov_b32_e32 v23, 0x358637bd
	s_mov_b32 s3, 0x9b00000
	s_mov_b32 s5, 0x9b01000
